# P6' d_out stores widened: permlane16/32 swaps so each store covers 64 contiguous bytes per row; + XCD-local seams (3us stagger) + P4/P6' epilogue rewrites
# speedup vs baseline: 1.0055x; 1.0023x over previous
.LBB0_677:
	s_lshl_b32 s3, s2, 8
	s_add_i32 s3, s3, s77
	v_add_u32_e32 v181, s3, v172
	v_lshl_add_u32 v185, v173, 3, s44
	v_lshlrev_b32_e32 v253, 2, v181
	v_lshlrev_b32_e32 v252, 2, v185
	v_lshlrev_b32_e32 v187, 12, v181
	v_lshl_add_u32 v187, v185, 1, v187
	v_lshlrev_b32_e32 v181, 13, v181
	s_lshl_b32 s3, s44, 2
	v_lshl_add_u32 v185, v173, 4, s3
	v_add_u32_e32 v185, v185, v181
	global_load_dword v164, v253, s[12:13]
	global_load_dword v165, v253, s[12:13] offset:64
	global_load_dword v166, v253, s[12:13] offset:128
	global_load_dword v167, v253, s[12:13] offset:192
	global_load_dword v168, v253, s[12:13] offset:512
	global_load_dword v169, v253, s[12:13] offset:576
	global_load_dword v170, v253, s[12:13] offset:640
	global_load_dword v171, v253, s[12:13] offset:704
	global_load_dwordx4 v[148:151], v252, s[14:15] offset:0
	global_load_dwordx4 v[152:155], v252, s[14:15] offset:16
	global_load_dwordx4 v[156:159], v252, s[14:15] offset:512
	global_load_dwordx4 v[160:163], v252, s[14:15] offset:528
	s_mov_b32 s98, s18
	s_mov_b32 s99, s19
	s_nop 0
	global_load_dwordx4 v[188:191], v187, s[98:99]
	global_load_dwordx4 v[192:195], v187, s[98:99] offset:256
	s_add_u32 s98, s18, 0x10000
	s_addc_u32 s99, s19, 0
	s_nop 0
	global_load_dwordx4 v[196:199], v187, s[98:99]
	global_load_dwordx4 v[200:203], v187, s[98:99] offset:256
	s_add_u32 s98, s18, 0x20000
	s_addc_u32 s99, s19, 0
	s_nop 0
	global_load_dwordx4 v[204:207], v187, s[98:99]
	global_load_dwordx4 v[208:211], v187, s[98:99] offset:256
	s_add_u32 s98, s18, 0x30000
	s_addc_u32 s99, s19, 0
	s_nop 0
	global_load_dwordx4 v[212:215], v187, s[98:99]
	global_load_dwordx4 v[216:219], v187, s[98:99] offset:256
	s_add_u32 s98, s18, 0x80000
	s_addc_u32 s99, s19, 0
	s_nop 0
	global_load_dwordx4 v[220:223], v187, s[98:99]
	global_load_dwordx4 v[224:227], v187, s[98:99] offset:256
	s_add_u32 s98, s18, 0x90000
	s_addc_u32 s99, s19, 0
	s_nop 0
	global_load_dwordx4 v[228:231], v187, s[98:99]
	global_load_dwordx4 v[232:235], v187, s[98:99] offset:256
	s_add_u32 s98, s18, 0xa0000
	s_addc_u32 s99, s19, 0
	s_nop 0
	global_load_dwordx4 v[236:239], v187, s[98:99]
	global_load_dwordx4 v[240:243], v187, s[98:99] offset:256
	s_add_u32 s98, s18, 0xb0000
	s_addc_u32 s99, s19, 0
	s_nop 0
	global_load_dwordx4 v[244:247], v187, s[98:99]
	global_load_dwordx4 v[248:251], v187, s[98:99] offset:256
	s_waitcnt vmcnt(15)
	v_fmamk_f32 v184, v164, 0x3a000000, v177
	v_rcp_f32_e32 v184, v184
	v_and_b32_e32 v129, 0xffff0000, v188
	v_lshlrev_b32_e32 v128, 16, v188
	v_and_b32_e32 v131, 0xffff0000, v189
	v_lshlrev_b32_e32 v130, 16, v189
	v_and_b32_e32 v133, 0xffff0000, v190
	v_lshlrev_b32_e32 v132, 16, v190
	v_and_b32_e32 v135, 0xffff0000, v191
	v_lshlrev_b32_e32 v134, 16, v191
	v_pk_mul_f32 v[128:129], v[148:149], v[128:129]
	v_pk_mul_f32 v[130:131], v[150:151], v[130:131]
	v_pk_mul_f32 v[132:133], v[152:153], v[132:133]
	v_pk_mul_f32 v[134:135], v[154:155], v[134:135]
	v_pk_fma_f32 v[124:125], v[124:125], v[184:185], v[128:129] op_sel_hi:[1,0,1]
	v_pk_fma_f32 v[126:127], v[126:127], v[184:185], v[130:131] op_sel_hi:[1,0,1]
	v_pk_fma_f32 v[120:121], v[120:121], v[184:185], v[132:133] op_sel_hi:[1,0,1]
	v_pk_fma_f32 v[122:123], v[122:123], v[184:185], v[134:135] op_sel_hi:[1,0,1]
	v_pk_mul_f32 v[182:183], v[124:125], v[124:125]
	v_pk_fma_f32 v[182:183], v[126:127], v[126:127], v[182:183]
	v_pk_fma_f32 v[182:183], v[120:121], v[120:121], v[182:183]
	v_pk_fma_f32 v[182:183], v[122:123], v[122:123], v[182:183]
	s_waitcnt vmcnt(14)
	v_and_b32_e32 v129, 0xffff0000, v192
	v_lshlrev_b32_e32 v128, 16, v192
	v_and_b32_e32 v131, 0xffff0000, v193
	v_lshlrev_b32_e32 v130, 16, v193
	v_and_b32_e32 v133, 0xffff0000, v194
	v_lshlrev_b32_e32 v132, 16, v194
	v_and_b32_e32 v135, 0xffff0000, v195
	v_lshlrev_b32_e32 v134, 16, v195
	v_pk_mul_f32 v[128:129], v[156:157], v[128:129]
	v_pk_mul_f32 v[130:131], v[158:159], v[130:131]
	v_pk_mul_f32 v[132:133], v[160:161], v[132:133]
	v_pk_mul_f32 v[134:135], v[162:163], v[134:135]
	v_pk_fma_f32 v[116:117], v[116:117], v[184:185], v[128:129] op_sel_hi:[1,0,1]
	v_pk_fma_f32 v[118:119], v[118:119], v[184:185], v[130:131] op_sel_hi:[1,0,1]
	v_pk_fma_f32 v[112:113], v[112:113], v[184:185], v[132:133] op_sel_hi:[1,0,1]
	v_pk_fma_f32 v[114:115], v[114:115], v[184:185], v[134:135] op_sel_hi:[1,0,1]
	v_pk_fma_f32 v[182:183], v[116:117], v[116:117], v[182:183]
	v_pk_fma_f32 v[182:183], v[118:119], v[118:119], v[182:183]
	v_pk_fma_f32 v[182:183], v[112:113], v[112:113], v[182:183]
	v_pk_fma_f32 v[182:183], v[114:115], v[114:115], v[182:183]
	v_add_f32_e32 v164, v182, v183
	s_waitcnt vmcnt(13)
	v_fmamk_f32 v184, v165, 0x3a000000, v177
	v_rcp_f32_e32 v184, v184
	v_and_b32_e32 v129, 0xffff0000, v196
	v_lshlrev_b32_e32 v128, 16, v196
	v_and_b32_e32 v131, 0xffff0000, v197
	v_lshlrev_b32_e32 v130, 16, v197
	v_and_b32_e32 v133, 0xffff0000, v198
	v_lshlrev_b32_e32 v132, 16, v198
	v_and_b32_e32 v135, 0xffff0000, v199
	v_lshlrev_b32_e32 v134, 16, v199
	v_pk_mul_f32 v[128:129], v[148:149], v[128:129]
	v_pk_mul_f32 v[130:131], v[150:151], v[130:131]
	v_pk_mul_f32 v[132:133], v[152:153], v[132:133]
	v_pk_mul_f32 v[134:135], v[154:155], v[134:135]
	v_pk_fma_f32 v[108:109], v[108:109], v[184:185], v[128:129] op_sel_hi:[1,0,1]
	v_pk_fma_f32 v[110:111], v[110:111], v[184:185], v[130:131] op_sel_hi:[1,0,1]
	v_pk_fma_f32 v[104:105], v[104:105], v[184:185], v[132:133] op_sel_hi:[1,0,1]
	v_pk_fma_f32 v[106:107], v[106:107], v[184:185], v[134:135] op_sel_hi:[1,0,1]
	v_pk_mul_f32 v[182:183], v[108:109], v[108:109]
	v_pk_fma_f32 v[182:183], v[110:111], v[110:111], v[182:183]
	v_pk_fma_f32 v[182:183], v[104:105], v[104:105], v[182:183]
	v_pk_fma_f32 v[182:183], v[106:107], v[106:107], v[182:183]
	s_waitcnt vmcnt(12)
	v_and_b32_e32 v129, 0xffff0000, v200
	v_lshlrev_b32_e32 v128, 16, v200
	v_and_b32_e32 v131, 0xffff0000, v201
	v_lshlrev_b32_e32 v130, 16, v201
	v_and_b32_e32 v133, 0xffff0000, v202
	v_lshlrev_b32_e32 v132, 16, v202
	v_and_b32_e32 v135, 0xffff0000, v203
	v_lshlrev_b32_e32 v134, 16, v203
	v_pk_mul_f32 v[128:129], v[156:157], v[128:129]
	v_pk_mul_f32 v[130:131], v[158:159], v[130:131]
	v_pk_mul_f32 v[132:133], v[160:161], v[132:133]
	v_pk_mul_f32 v[134:135], v[162:163], v[134:135]
	v_pk_fma_f32 v[100:101], v[100:101], v[184:185], v[128:129] op_sel_hi:[1,0,1]
	v_pk_fma_f32 v[102:103], v[102:103], v[184:185], v[130:131] op_sel_hi:[1,0,1]
	v_pk_fma_f32 v[96:97], v[96:97], v[184:185], v[132:133] op_sel_hi:[1,0,1]
	v_pk_fma_f32 v[98:99], v[98:99], v[184:185], v[134:135] op_sel_hi:[1,0,1]
	v_pk_fma_f32 v[182:183], v[100:101], v[100:101], v[182:183]
	v_pk_fma_f32 v[182:183], v[102:103], v[102:103], v[182:183]
	v_pk_fma_f32 v[182:183], v[96:97], v[96:97], v[182:183]
	v_pk_fma_f32 v[182:183], v[98:99], v[98:99], v[182:183]
	v_add_f32_e32 v165, v182, v183
	s_waitcnt vmcnt(11)
	v_fmamk_f32 v184, v166, 0x3a000000, v177
	v_rcp_f32_e32 v184, v184
	v_and_b32_e32 v129, 0xffff0000, v204
	v_lshlrev_b32_e32 v128, 16, v204
	v_and_b32_e32 v131, 0xffff0000, v205
	v_lshlrev_b32_e32 v130, 16, v205
	v_and_b32_e32 v133, 0xffff0000, v206
	v_lshlrev_b32_e32 v132, 16, v206
	v_and_b32_e32 v135, 0xffff0000, v207
	v_lshlrev_b32_e32 v134, 16, v207
	v_pk_mul_f32 v[128:129], v[148:149], v[128:129]
	v_pk_mul_f32 v[130:131], v[150:151], v[130:131]
	v_pk_mul_f32 v[132:133], v[152:153], v[132:133]
	v_pk_mul_f32 v[134:135], v[154:155], v[134:135]
	v_pk_fma_f32 v[92:93], v[92:93], v[184:185], v[128:129] op_sel_hi:[1,0,1]
	v_pk_fma_f32 v[94:95], v[94:95], v[184:185], v[130:131] op_sel_hi:[1,0,1]
	v_pk_fma_f32 v[88:89], v[88:89], v[184:185], v[132:133] op_sel_hi:[1,0,1]
	v_pk_fma_f32 v[90:91], v[90:91], v[184:185], v[134:135] op_sel_hi:[1,0,1]
	v_pk_mul_f32 v[182:183], v[92:93], v[92:93]
	v_pk_fma_f32 v[182:183], v[94:95], v[94:95], v[182:183]
	v_pk_fma_f32 v[182:183], v[88:89], v[88:89], v[182:183]
	v_pk_fma_f32 v[182:183], v[90:91], v[90:91], v[182:183]
	s_waitcnt vmcnt(10)
	v_and_b32_e32 v129, 0xffff0000, v208
	v_lshlrev_b32_e32 v128, 16, v208
	v_and_b32_e32 v131, 0xffff0000, v209
	v_lshlrev_b32_e32 v130, 16, v209
	v_and_b32_e32 v133, 0xffff0000, v210
	v_lshlrev_b32_e32 v132, 16, v210
	v_and_b32_e32 v135, 0xffff0000, v211
	v_lshlrev_b32_e32 v134, 16, v211
	v_pk_mul_f32 v[128:129], v[156:157], v[128:129]
	v_pk_mul_f32 v[130:131], v[158:159], v[130:131]
	v_pk_mul_f32 v[132:133], v[160:161], v[132:133]
	v_pk_mul_f32 v[134:135], v[162:163], v[134:135]
	v_pk_fma_f32 v[84:85], v[84:85], v[184:185], v[128:129] op_sel_hi:[1,0,1]
	v_pk_fma_f32 v[86:87], v[86:87], v[184:185], v[130:131] op_sel_hi:[1,0,1]
	v_pk_fma_f32 v[80:81], v[80:81], v[184:185], v[132:133] op_sel_hi:[1,0,1]
	v_pk_fma_f32 v[82:83], v[82:83], v[184:185], v[134:135] op_sel_hi:[1,0,1]
	v_pk_fma_f32 v[182:183], v[84:85], v[84:85], v[182:183]
	v_pk_fma_f32 v[182:183], v[86:87], v[86:87], v[182:183]
	v_pk_fma_f32 v[182:183], v[80:81], v[80:81], v[182:183]
	v_pk_fma_f32 v[182:183], v[82:83], v[82:83], v[182:183]
	v_add_f32_e32 v166, v182, v183
	s_waitcnt vmcnt(9)
	v_fmamk_f32 v184, v167, 0x3a000000, v177
	v_rcp_f32_e32 v184, v184
	v_and_b32_e32 v129, 0xffff0000, v212
	v_lshlrev_b32_e32 v128, 16, v212
	v_and_b32_e32 v131, 0xffff0000, v213
	v_lshlrev_b32_e32 v130, 16, v213
	v_and_b32_e32 v133, 0xffff0000, v214
	v_lshlrev_b32_e32 v132, 16, v214
	v_and_b32_e32 v135, 0xffff0000, v215
	v_lshlrev_b32_e32 v134, 16, v215
	v_pk_mul_f32 v[128:129], v[148:149], v[128:129]
	v_pk_mul_f32 v[130:131], v[150:151], v[130:131]
	v_pk_mul_f32 v[132:133], v[152:153], v[132:133]
	v_pk_mul_f32 v[134:135], v[154:155], v[134:135]
	v_pk_fma_f32 v[76:77], v[76:77], v[184:185], v[128:129] op_sel_hi:[1,0,1]
	v_pk_fma_f32 v[78:79], v[78:79], v[184:185], v[130:131] op_sel_hi:[1,0,1]
	v_pk_fma_f32 v[72:73], v[72:73], v[184:185], v[132:133] op_sel_hi:[1,0,1]
	v_pk_fma_f32 v[74:75], v[74:75], v[184:185], v[134:135] op_sel_hi:[1,0,1]
	v_pk_mul_f32 v[182:183], v[76:77], v[76:77]
	v_pk_fma_f32 v[182:183], v[78:79], v[78:79], v[182:183]
	v_pk_fma_f32 v[182:183], v[72:73], v[72:73], v[182:183]
	v_pk_fma_f32 v[182:183], v[74:75], v[74:75], v[182:183]
	s_waitcnt vmcnt(8)
	v_and_b32_e32 v129, 0xffff0000, v216
	v_lshlrev_b32_e32 v128, 16, v216
	v_and_b32_e32 v131, 0xffff0000, v217
	v_lshlrev_b32_e32 v130, 16, v217
	v_and_b32_e32 v133, 0xffff0000, v218
	v_lshlrev_b32_e32 v132, 16, v218
	v_and_b32_e32 v135, 0xffff0000, v219
	v_lshlrev_b32_e32 v134, 16, v219
	v_pk_mul_f32 v[128:129], v[156:157], v[128:129]
	v_pk_mul_f32 v[130:131], v[158:159], v[130:131]
	v_pk_mul_f32 v[132:133], v[160:161], v[132:133]
	v_pk_mul_f32 v[134:135], v[162:163], v[134:135]
	v_pk_fma_f32 v[68:69], v[68:69], v[184:185], v[128:129] op_sel_hi:[1,0,1]
	v_pk_fma_f32 v[70:71], v[70:71], v[184:185], v[130:131] op_sel_hi:[1,0,1]
	v_pk_fma_f32 v[64:65], v[64:65], v[184:185], v[132:133] op_sel_hi:[1,0,1]
	v_pk_fma_f32 v[66:67], v[66:67], v[184:185], v[134:135] op_sel_hi:[1,0,1]
	v_pk_fma_f32 v[182:183], v[68:69], v[68:69], v[182:183]
	v_pk_fma_f32 v[182:183], v[70:71], v[70:71], v[182:183]
	v_pk_fma_f32 v[182:183], v[64:65], v[64:65], v[182:183]
	v_pk_fma_f32 v[182:183], v[66:67], v[66:67], v[182:183]
	v_add_f32_e32 v167, v182, v183
	s_waitcnt vmcnt(7)
	v_fmamk_f32 v184, v168, 0x3a000000, v177
	v_rcp_f32_e32 v184, v184
	v_and_b32_e32 v129, 0xffff0000, v220
	v_lshlrev_b32_e32 v128, 16, v220
	v_and_b32_e32 v131, 0xffff0000, v221
	v_lshlrev_b32_e32 v130, 16, v221
	v_and_b32_e32 v133, 0xffff0000, v222
	v_lshlrev_b32_e32 v132, 16, v222
	v_and_b32_e32 v135, 0xffff0000, v223
	v_lshlrev_b32_e32 v134, 16, v223
	v_pk_mul_f32 v[128:129], v[148:149], v[128:129]
	v_pk_mul_f32 v[130:131], v[150:151], v[130:131]
	v_pk_mul_f32 v[132:133], v[152:153], v[132:133]
	v_pk_mul_f32 v[134:135], v[154:155], v[134:135]
	v_pk_fma_f32 v[60:61], v[60:61], v[184:185], v[128:129] op_sel_hi:[1,0,1]
	v_pk_fma_f32 v[62:63], v[62:63], v[184:185], v[130:131] op_sel_hi:[1,0,1]
	v_pk_fma_f32 v[56:57], v[56:57], v[184:185], v[132:133] op_sel_hi:[1,0,1]
	v_pk_fma_f32 v[58:59], v[58:59], v[184:185], v[134:135] op_sel_hi:[1,0,1]
	v_pk_mul_f32 v[182:183], v[60:61], v[60:61]
	v_pk_fma_f32 v[182:183], v[62:63], v[62:63], v[182:183]
	v_pk_fma_f32 v[182:183], v[56:57], v[56:57], v[182:183]
	v_pk_fma_f32 v[182:183], v[58:59], v[58:59], v[182:183]
	s_waitcnt vmcnt(6)
	v_and_b32_e32 v129, 0xffff0000, v224
	v_lshlrev_b32_e32 v128, 16, v224
	v_and_b32_e32 v131, 0xffff0000, v225
	v_lshlrev_b32_e32 v130, 16, v225
	v_and_b32_e32 v133, 0xffff0000, v226
	v_lshlrev_b32_e32 v132, 16, v226
	v_and_b32_e32 v135, 0xffff0000, v227
	v_lshlrev_b32_e32 v134, 16, v227
	v_pk_mul_f32 v[128:129], v[156:157], v[128:129]
	v_pk_mul_f32 v[130:131], v[158:159], v[130:131]
	v_pk_mul_f32 v[132:133], v[160:161], v[132:133]
	v_pk_mul_f32 v[134:135], v[162:163], v[134:135]
	v_pk_fma_f32 v[52:53], v[52:53], v[184:185], v[128:129] op_sel_hi:[1,0,1]
	v_pk_fma_f32 v[54:55], v[54:55], v[184:185], v[130:131] op_sel_hi:[1,0,1]
	v_pk_fma_f32 v[48:49], v[48:49], v[184:185], v[132:133] op_sel_hi:[1,0,1]
	v_pk_fma_f32 v[50:51], v[50:51], v[184:185], v[134:135] op_sel_hi:[1,0,1]
	v_pk_fma_f32 v[182:183], v[52:53], v[52:53], v[182:183]
	v_pk_fma_f32 v[182:183], v[54:55], v[54:55], v[182:183]
	v_pk_fma_f32 v[182:183], v[48:49], v[48:49], v[182:183]
	v_pk_fma_f32 v[182:183], v[50:51], v[50:51], v[182:183]
	v_add_f32_e32 v168, v182, v183
	s_waitcnt vmcnt(5)
	v_fmamk_f32 v184, v169, 0x3a000000, v177
	v_rcp_f32_e32 v184, v184
	v_and_b32_e32 v129, 0xffff0000, v228
	v_lshlrev_b32_e32 v128, 16, v228
	v_and_b32_e32 v131, 0xffff0000, v229
	v_lshlrev_b32_e32 v130, 16, v229
	v_and_b32_e32 v133, 0xffff0000, v230
	v_lshlrev_b32_e32 v132, 16, v230
	v_and_b32_e32 v135, 0xffff0000, v231
	v_lshlrev_b32_e32 v134, 16, v231
	v_pk_mul_f32 v[128:129], v[148:149], v[128:129]
	v_pk_mul_f32 v[130:131], v[150:151], v[130:131]
	v_pk_mul_f32 v[132:133], v[152:153], v[132:133]
	v_pk_mul_f32 v[134:135], v[154:155], v[134:135]
	v_pk_fma_f32 v[44:45], v[44:45], v[184:185], v[128:129] op_sel_hi:[1,0,1]
	v_pk_fma_f32 v[46:47], v[46:47], v[184:185], v[130:131] op_sel_hi:[1,0,1]
	v_pk_fma_f32 v[40:41], v[40:41], v[184:185], v[132:133] op_sel_hi:[1,0,1]
	v_pk_fma_f32 v[42:43], v[42:43], v[184:185], v[134:135] op_sel_hi:[1,0,1]
	v_pk_mul_f32 v[182:183], v[44:45], v[44:45]
	v_pk_fma_f32 v[182:183], v[46:47], v[46:47], v[182:183]
	v_pk_fma_f32 v[182:183], v[40:41], v[40:41], v[182:183]
	v_pk_fma_f32 v[182:183], v[42:43], v[42:43], v[182:183]
	s_waitcnt vmcnt(4)
	v_and_b32_e32 v129, 0xffff0000, v232
	v_lshlrev_b32_e32 v128, 16, v232
	v_and_b32_e32 v131, 0xffff0000, v233
	v_lshlrev_b32_e32 v130, 16, v233
	v_and_b32_e32 v133, 0xffff0000, v234
	v_lshlrev_b32_e32 v132, 16, v234
	v_and_b32_e32 v135, 0xffff0000, v235
	v_lshlrev_b32_e32 v134, 16, v235
	v_pk_mul_f32 v[128:129], v[156:157], v[128:129]
	v_pk_mul_f32 v[130:131], v[158:159], v[130:131]
	v_pk_mul_f32 v[132:133], v[160:161], v[132:133]
	v_pk_mul_f32 v[134:135], v[162:163], v[134:135]
	v_pk_fma_f32 v[36:37], v[36:37], v[184:185], v[128:129] op_sel_hi:[1,0,1]
	v_pk_fma_f32 v[38:39], v[38:39], v[184:185], v[130:131] op_sel_hi:[1,0,1]
	v_pk_fma_f32 v[32:33], v[32:33], v[184:185], v[132:133] op_sel_hi:[1,0,1]
	v_pk_fma_f32 v[34:35], v[34:35], v[184:185], v[134:135] op_sel_hi:[1,0,1]
	v_pk_fma_f32 v[182:183], v[36:37], v[36:37], v[182:183]
	v_pk_fma_f32 v[182:183], v[38:39], v[38:39], v[182:183]
	v_pk_fma_f32 v[182:183], v[32:33], v[32:33], v[182:183]
	v_pk_fma_f32 v[182:183], v[34:35], v[34:35], v[182:183]
	v_add_f32_e32 v169, v182, v183
	s_waitcnt vmcnt(3)
	v_fmamk_f32 v184, v170, 0x3a000000, v177
	v_rcp_f32_e32 v184, v184
	v_and_b32_e32 v129, 0xffff0000, v236
	v_lshlrev_b32_e32 v128, 16, v236
	v_and_b32_e32 v131, 0xffff0000, v237
	v_lshlrev_b32_e32 v130, 16, v237
	v_and_b32_e32 v133, 0xffff0000, v238
	v_lshlrev_b32_e32 v132, 16, v238
	v_and_b32_e32 v135, 0xffff0000, v239
	v_lshlrev_b32_e32 v134, 16, v239
	v_pk_mul_f32 v[128:129], v[148:149], v[128:129]
	v_pk_mul_f32 v[130:131], v[150:151], v[130:131]
	v_pk_mul_f32 v[132:133], v[152:153], v[132:133]
	v_pk_mul_f32 v[134:135], v[154:155], v[134:135]
	v_pk_fma_f32 v[28:29], v[28:29], v[184:185], v[128:129] op_sel_hi:[1,0,1]
	v_pk_fma_f32 v[30:31], v[30:31], v[184:185], v[130:131] op_sel_hi:[1,0,1]
	v_pk_fma_f32 v[24:25], v[24:25], v[184:185], v[132:133] op_sel_hi:[1,0,1]
	v_pk_fma_f32 v[26:27], v[26:27], v[184:185], v[134:135] op_sel_hi:[1,0,1]
	v_pk_mul_f32 v[182:183], v[28:29], v[28:29]
	v_pk_fma_f32 v[182:183], v[30:31], v[30:31], v[182:183]
	v_pk_fma_f32 v[182:183], v[24:25], v[24:25], v[182:183]
	v_pk_fma_f32 v[182:183], v[26:27], v[26:27], v[182:183]
	s_waitcnt vmcnt(2)
	v_and_b32_e32 v129, 0xffff0000, v240
	v_lshlrev_b32_e32 v128, 16, v240
	v_and_b32_e32 v131, 0xffff0000, v241
	v_lshlrev_b32_e32 v130, 16, v241
	v_and_b32_e32 v133, 0xffff0000, v242
	v_lshlrev_b32_e32 v132, 16, v242
	v_and_b32_e32 v135, 0xffff0000, v243
	v_lshlrev_b32_e32 v134, 16, v243
	v_pk_mul_f32 v[128:129], v[156:157], v[128:129]
	v_pk_mul_f32 v[130:131], v[158:159], v[130:131]
	v_pk_mul_f32 v[132:133], v[160:161], v[132:133]
	v_pk_mul_f32 v[134:135], v[162:163], v[134:135]
	v_pk_fma_f32 v[20:21], v[20:21], v[184:185], v[128:129] op_sel_hi:[1,0,1]
	v_pk_fma_f32 v[22:23], v[22:23], v[184:185], v[130:131] op_sel_hi:[1,0,1]
	v_pk_fma_f32 v[16:17], v[16:17], v[184:185], v[132:133] op_sel_hi:[1,0,1]
	v_pk_fma_f32 v[18:19], v[18:19], v[184:185], v[134:135] op_sel_hi:[1,0,1]
	v_pk_fma_f32 v[182:183], v[20:21], v[20:21], v[182:183]
	v_pk_fma_f32 v[182:183], v[22:23], v[22:23], v[182:183]
	v_pk_fma_f32 v[182:183], v[16:17], v[16:17], v[182:183]
	v_pk_fma_f32 v[182:183], v[18:19], v[18:19], v[182:183]
	v_add_f32_e32 v170, v182, v183
	s_waitcnt vmcnt(1)
	v_fmamk_f32 v184, v171, 0x3a000000, v177
	v_rcp_f32_e32 v184, v184
	v_and_b32_e32 v129, 0xffff0000, v244
	v_lshlrev_b32_e32 v128, 16, v244
	v_and_b32_e32 v131, 0xffff0000, v245
	v_lshlrev_b32_e32 v130, 16, v245
	v_and_b32_e32 v133, 0xffff0000, v246
	v_lshlrev_b32_e32 v132, 16, v246
	v_and_b32_e32 v135, 0xffff0000, v247
	v_lshlrev_b32_e32 v134, 16, v247
	v_pk_mul_f32 v[128:129], v[148:149], v[128:129]
	v_pk_mul_f32 v[130:131], v[150:151], v[130:131]
	v_pk_mul_f32 v[132:133], v[152:153], v[132:133]
	v_pk_mul_f32 v[134:135], v[154:155], v[134:135]
	v_pk_fma_f32 v[12:13], v[12:13], v[184:185], v[128:129] op_sel_hi:[1,0,1]
	v_pk_fma_f32 v[14:15], v[14:15], v[184:185], v[130:131] op_sel_hi:[1,0,1]
	v_pk_fma_f32 v[8:9], v[8:9], v[184:185], v[132:133] op_sel_hi:[1,0,1]
	v_pk_fma_f32 v[10:11], v[10:11], v[184:185], v[134:135] op_sel_hi:[1,0,1]
	v_pk_mul_f32 v[182:183], v[12:13], v[12:13]
	v_pk_fma_f32 v[182:183], v[14:15], v[14:15], v[182:183]
	v_pk_fma_f32 v[182:183], v[8:9], v[8:9], v[182:183]
	v_pk_fma_f32 v[182:183], v[10:11], v[10:11], v[182:183]
	s_waitcnt vmcnt(0)
	v_and_b32_e32 v129, 0xffff0000, v248
	v_lshlrev_b32_e32 v128, 16, v248
	v_and_b32_e32 v131, 0xffff0000, v249
	v_lshlrev_b32_e32 v130, 16, v249
	v_and_b32_e32 v133, 0xffff0000, v250
	v_lshlrev_b32_e32 v132, 16, v250
	v_and_b32_e32 v135, 0xffff0000, v251
	v_lshlrev_b32_e32 v134, 16, v251
	v_pk_mul_f32 v[128:129], v[156:157], v[128:129]
	v_pk_mul_f32 v[130:131], v[158:159], v[130:131]
	v_pk_mul_f32 v[132:133], v[160:161], v[132:133]
	v_pk_mul_f32 v[134:135], v[162:163], v[134:135]
	v_pk_fma_f32 v[4:5], v[4:5], v[184:185], v[128:129] op_sel_hi:[1,0,1]
	v_pk_fma_f32 v[6:7], v[6:7], v[184:185], v[130:131] op_sel_hi:[1,0,1]
	v_pk_fma_f32 v[0:1], v[0:1], v[184:185], v[132:133] op_sel_hi:[1,0,1]
	v_pk_fma_f32 v[2:3], v[2:3], v[184:185], v[134:135] op_sel_hi:[1,0,1]
	v_pk_fma_f32 v[182:183], v[4:5], v[4:5], v[182:183]
	v_pk_fma_f32 v[182:183], v[6:7], v[6:7], v[182:183]
	v_pk_fma_f32 v[182:183], v[0:1], v[0:1], v[182:183]
	v_pk_fma_f32 v[182:183], v[2:3], v[2:3], v[182:183]
	v_add_f32_e32 v171, v182, v183
	global_load_dwordx4 v[148:151], v252, s[86:87] offset:0
	global_load_dwordx4 v[152:155], v252, s[86:87] offset:16
	global_load_dwordx4 v[156:159], v252, s[86:87] offset:512
	global_load_dwordx4 v[160:163], v252, s[86:87] offset:528
	v_xor_b32_e32 v128, 16, v186
	v_xor_b32_e32 v129, 32, v186
	v_lshlrev_b32_e32 v128, 2, v128
	v_lshlrev_b32_e32 v129, 2, v129
	ds_bpermute_b32 v188, v128, v164
	ds_bpermute_b32 v189, v128, v165
	ds_bpermute_b32 v190, v128, v166
	ds_bpermute_b32 v191, v128, v167
	ds_bpermute_b32 v192, v128, v168
	ds_bpermute_b32 v193, v128, v169
	ds_bpermute_b32 v194, v128, v170
	ds_bpermute_b32 v195, v128, v171
	s_waitcnt lgkmcnt(7)
	v_add_f32_e32 v164, v164, v188
	s_waitcnt lgkmcnt(6)
	v_add_f32_e32 v165, v165, v189
	s_waitcnt lgkmcnt(5)
	v_add_f32_e32 v166, v166, v190
	s_waitcnt lgkmcnt(4)
	v_add_f32_e32 v167, v167, v191
	s_waitcnt lgkmcnt(3)
	v_add_f32_e32 v168, v168, v192
	s_waitcnt lgkmcnt(2)
	v_add_f32_e32 v169, v169, v193
	s_waitcnt lgkmcnt(1)
	v_add_f32_e32 v170, v170, v194
	s_waitcnt lgkmcnt(0)
	v_add_f32_e32 v171, v171, v195
	ds_bpermute_b32 v188, v129, v164
	ds_bpermute_b32 v189, v129, v165
	ds_bpermute_b32 v190, v129, v166
	ds_bpermute_b32 v191, v129, v167
	ds_bpermute_b32 v192, v129, v168
	ds_bpermute_b32 v193, v129, v169
	ds_bpermute_b32 v194, v129, v170
	ds_bpermute_b32 v195, v129, v171
	v_cmp_eq_u32_e32 vcc, 0, v173
	s_and_saveexec_b64 s[36:37], vcc
	s_waitcnt lgkmcnt(7)
	v_add_f32_e32 v164, v164, v188
	global_atomic_add_f32 v253, v164, s[16:17]
	s_waitcnt lgkmcnt(6)
	v_add_f32_e32 v165, v165, v189
	global_atomic_add_f32 v253, v165, s[16:17] offset:64
	s_waitcnt lgkmcnt(5)
	v_add_f32_e32 v166, v166, v190
	global_atomic_add_f32 v253, v166, s[16:17] offset:128
	s_waitcnt lgkmcnt(4)
	v_add_f32_e32 v167, v167, v191
	global_atomic_add_f32 v253, v167, s[16:17] offset:192
	s_waitcnt lgkmcnt(3)
	v_add_f32_e32 v168, v168, v192
	global_atomic_add_f32 v253, v168, s[16:17] offset:512
	s_waitcnt lgkmcnt(2)
	v_add_f32_e32 v169, v169, v193
	global_atomic_add_f32 v253, v169, s[16:17] offset:576
	s_waitcnt lgkmcnt(1)
	v_add_f32_e32 v170, v170, v194
	global_atomic_add_f32 v253, v170, s[16:17] offset:640
	s_waitcnt lgkmcnt(0)
	v_add_f32_e32 v171, v171, v195
	global_atomic_add_f32 v253, v171, s[16:17] offset:704
	s_or_b64 exec, exec, s[36:37]
	s_lshl_b32 s2, s2, 6
	s_ashr_i32 s3, s2, 31
	s_lshl_b64 s[2:3], s[2:3], 2
	s_waitcnt vmcnt(0)
	s_add_u32 s24, s42, s2
	s_addc_u32 s25, s43, s3
	v_cmp_eq_u32_e32 vcc, 0, v173
	v_cmp_eq_u32_e64 s[2:3], 0, v172
	s_and_b64 s[30:31], s[2:3], vcc
	v_mov_b32_e32 v181, 1
	s_and_saveexec_b64 s[2:3], s[30:31]
	global_atomic_add v139, v181, s[24:25]
	s_or_b64 exec, exec, s[2:3]
	s_mov_b32 s29, 0x100001
	s_branch .Lp6_spin

.Lp6_part2:
	global_load_dword v164, v253, s[16:17] sc1
	global_load_dword v165, v253, s[16:17] offset:64 sc1
	global_load_dword v166, v253, s[16:17] offset:128 sc1
	global_load_dword v167, v253, s[16:17] offset:192 sc1
	global_load_dword v168, v253, s[16:17] offset:512 sc1
	global_load_dword v169, v253, s[16:17] offset:576 sc1
	global_load_dword v170, v253, s[16:17] offset:640 sc1
	global_load_dword v171, v253, s[16:17] offset:704 sc1
	s_waitcnt vmcnt(7)
	v_fmamk_f32 v128, v164, 0x3a000000, v177
	v_mul_f32_e32 v129, 0x4f800000, v128
	v_cmp_gt_f32_e32 vcc, s9, v128
	s_nop 1
	v_cndmask_b32_e32 v128, v128, v129, vcc
	v_sqrt_f32_e32 v129, v128
	s_nop 0
	v_add_u32_e32 v130, -1, v129
	v_add_u32_e32 v131, 1, v129
	v_fma_f32 v132, -v130, v129, v128
	v_fma_f32 v133, -v131, v129, v128
	v_cmp_ge_f32_e64 s[2:3], 0, v132
	s_nop 1
	v_cndmask_b32_e64 v129, v129, v130, s[2:3]
	v_cmp_lt_f32_e64 s[2:3], 0, v133
	s_nop 1
	v_cndmask_b32_e64 v129, v129, v131, s[2:3]
	v_mul_f32_e32 v130, 0x37800000, v129
	v_cndmask_b32_e32 v129, v129, v130, vcc
	v_cmp_class_f32_e32 vcc, v128, v178
	s_nop 1
	v_cndmask_b32_e32 v128, v129, v128, vcc
	v_div_scale_f32 v129, s[2:3], v128, v128, 1.0
	v_rcp_f32_e32 v130, v129
	v_div_scale_f32 v131, vcc, 1.0, v128, 1.0
	v_fma_f32 v132, -v129, v130, 1.0
	v_fmac_f32_e32 v130, v132, v130
	v_mul_f32_e32 v132, v131, v130
	v_fma_f32 v133, -v129, v132, v131
	v_fmac_f32_e32 v132, v133, v130
	v_fma_f32 v129, -v129, v132, v131
	v_div_fmas_f32 v129, v129, v130, v132
	v_div_fixup_f32 v184, v129, v128, 1.0
	s_mov_b32 s100, s64
	s_mov_b32 s101, s65
	v_pk_mul_f32 v[188:189], v[124:125], v[184:185] op_sel_hi:[1,0]
	v_pk_mul_f32 v[190:191], v[126:127], v[184:185] op_sel_hi:[1,0]
	v_pk_mul_f32 v[192:193], v[120:121], v[184:185] op_sel_hi:[1,0]
	v_pk_mul_f32 v[194:195], v[122:123], v[184:185] op_sel_hi:[1,0]
	v_pk_mul_f32 v[188:189], v[148:149], v[188:189]
	v_pk_mul_f32 v[190:191], v[150:151], v[190:191]
	v_pk_mul_f32 v[192:193], v[152:153], v[192:193]
	v_pk_mul_f32 v[194:195], v[154:155], v[194:195]
	s_nop 1
	v_permlane16_swap_b32_e32 v188, v192
	v_permlane16_swap_b32_e32 v189, v193
	v_permlane16_swap_b32_e32 v190, v194
	v_permlane16_swap_b32_e32 v191, v195
	v_permlane32_swap_b32_e32 v188, v192
	v_permlane32_swap_b32_e32 v189, v193
	v_permlane32_swap_b32_e32 v190, v194
	v_permlane32_swap_b32_e32 v191, v195
	s_nop 1
	global_store_dwordx4 v185, v[188:191], s[100:101] offset:0
	global_store_dwordx4 v185, v[192:195], s[100:101] offset:64
	v_pk_mul_f32 v[196:197], v[116:117], v[184:185] op_sel_hi:[1,0]
	v_pk_mul_f32 v[198:199], v[118:119], v[184:185] op_sel_hi:[1,0]
	v_pk_mul_f32 v[200:201], v[112:113], v[184:185] op_sel_hi:[1,0]
	v_pk_mul_f32 v[202:203], v[114:115], v[184:185] op_sel_hi:[1,0]
	v_pk_mul_f32 v[196:197], v[156:157], v[196:197]
	v_pk_mul_f32 v[198:199], v[158:159], v[198:199]
	v_pk_mul_f32 v[200:201], v[160:161], v[200:201]
	v_pk_mul_f32 v[202:203], v[162:163], v[202:203]
	s_nop 1
	v_permlane16_swap_b32_e32 v196, v200
	v_permlane16_swap_b32_e32 v197, v201
	v_permlane16_swap_b32_e32 v198, v202
	v_permlane16_swap_b32_e32 v199, v203
	v_permlane32_swap_b32_e32 v196, v200
	v_permlane32_swap_b32_e32 v197, v201
	v_permlane32_swap_b32_e32 v198, v202
	v_permlane32_swap_b32_e32 v199, v203
	s_nop 1
	global_store_dwordx4 v185, v[196:199], s[100:101] offset:512
	global_store_dwordx4 v185, v[200:203], s[100:101] offset:576
	s_waitcnt vmcnt(10)
	v_fmamk_f32 v128, v165, 0x3a000000, v177
	v_mul_f32_e32 v129, 0x4f800000, v128
	v_cmp_gt_f32_e32 vcc, s9, v128
	s_nop 1
	v_cndmask_b32_e32 v128, v128, v129, vcc
	v_sqrt_f32_e32 v129, v128
	s_nop 0
	v_add_u32_e32 v130, -1, v129
	v_add_u32_e32 v131, 1, v129
	v_fma_f32 v132, -v130, v129, v128
	v_fma_f32 v133, -v131, v129, v128
	v_cmp_ge_f32_e64 s[2:3], 0, v132
	s_nop 1
	v_cndmask_b32_e64 v129, v129, v130, s[2:3]
	v_cmp_lt_f32_e64 s[2:3], 0, v133
	s_nop 1
	v_cndmask_b32_e64 v129, v129, v131, s[2:3]
	v_mul_f32_e32 v130, 0x37800000, v129
	v_cndmask_b32_e32 v129, v129, v130, vcc
	v_cmp_class_f32_e32 vcc, v128, v178
	s_nop 1
	v_cndmask_b32_e32 v128, v129, v128, vcc
	v_div_scale_f32 v129, s[2:3], v128, v128, 1.0
	v_rcp_f32_e32 v130, v129
	v_div_scale_f32 v131, vcc, 1.0, v128, 1.0
	v_fma_f32 v132, -v129, v130, 1.0
	v_fmac_f32_e32 v130, v132, v130
	v_mul_f32_e32 v132, v131, v130
	v_fma_f32 v133, -v129, v132, v131
	v_fmac_f32_e32 v132, v133, v130
	v_fma_f32 v129, -v129, v132, v131
	v_div_fmas_f32 v129, v129, v130, v132
	v_div_fixup_f32 v184, v129, v128, 1.0
	s_add_u32 s100, s64, 0x20000
	s_addc_u32 s101, s65, 0
	v_pk_mul_f32 v[204:205], v[108:109], v[184:185] op_sel_hi:[1,0]
	v_pk_mul_f32 v[206:207], v[110:111], v[184:185] op_sel_hi:[1,0]
	v_pk_mul_f32 v[208:209], v[104:105], v[184:185] op_sel_hi:[1,0]
	v_pk_mul_f32 v[210:211], v[106:107], v[184:185] op_sel_hi:[1,0]
	v_pk_mul_f32 v[204:205], v[148:149], v[204:205]
	v_pk_mul_f32 v[206:207], v[150:151], v[206:207]
	v_pk_mul_f32 v[208:209], v[152:153], v[208:209]
	v_pk_mul_f32 v[210:211], v[154:155], v[210:211]
	s_nop 1
	v_permlane16_swap_b32_e32 v204, v208
	v_permlane16_swap_b32_e32 v205, v209
	v_permlane16_swap_b32_e32 v206, v210
	v_permlane16_swap_b32_e32 v207, v211
	v_permlane32_swap_b32_e32 v204, v208
	v_permlane32_swap_b32_e32 v205, v209
	v_permlane32_swap_b32_e32 v206, v210
	v_permlane32_swap_b32_e32 v207, v211
	s_nop 1
	global_store_dwordx4 v185, v[204:207], s[100:101] offset:0
	global_store_dwordx4 v185, v[208:211], s[100:101] offset:64
	v_pk_mul_f32 v[212:213], v[100:101], v[184:185] op_sel_hi:[1,0]
	v_pk_mul_f32 v[214:215], v[102:103], v[184:185] op_sel_hi:[1,0]
	v_pk_mul_f32 v[216:217], v[96:97], v[184:185] op_sel_hi:[1,0]
	v_pk_mul_f32 v[218:219], v[98:99], v[184:185] op_sel_hi:[1,0]
	v_pk_mul_f32 v[212:213], v[156:157], v[212:213]
	v_pk_mul_f32 v[214:215], v[158:159], v[214:215]
	v_pk_mul_f32 v[216:217], v[160:161], v[216:217]
	v_pk_mul_f32 v[218:219], v[162:163], v[218:219]
	s_nop 1
	v_permlane16_swap_b32_e32 v212, v216
	v_permlane16_swap_b32_e32 v213, v217
	v_permlane16_swap_b32_e32 v214, v218
	v_permlane16_swap_b32_e32 v215, v219
	v_permlane32_swap_b32_e32 v212, v216
	v_permlane32_swap_b32_e32 v213, v217
	v_permlane32_swap_b32_e32 v214, v218
	v_permlane32_swap_b32_e32 v215, v219
	s_nop 1
	global_store_dwordx4 v185, v[212:215], s[100:101] offset:512
	global_store_dwordx4 v185, v[216:219], s[100:101] offset:576
	s_waitcnt vmcnt(13)
	v_fmamk_f32 v128, v166, 0x3a000000, v177
	v_mul_f32_e32 v129, 0x4f800000, v128
	v_cmp_gt_f32_e32 vcc, s9, v128
	s_nop 1
	v_cndmask_b32_e32 v128, v128, v129, vcc
	v_sqrt_f32_e32 v129, v128
	s_nop 0
	v_add_u32_e32 v130, -1, v129
	v_add_u32_e32 v131, 1, v129
	v_fma_f32 v132, -v130, v129, v128
	v_fma_f32 v133, -v131, v129, v128
	v_cmp_ge_f32_e64 s[2:3], 0, v132
	s_nop 1
	v_cndmask_b32_e64 v129, v129, v130, s[2:3]
	v_cmp_lt_f32_e64 s[2:3], 0, v133
	s_nop 1
	v_cndmask_b32_e64 v129, v129, v131, s[2:3]
	v_mul_f32_e32 v130, 0x37800000, v129
	v_cndmask_b32_e32 v129, v129, v130, vcc
	v_cmp_class_f32_e32 vcc, v128, v178
	s_nop 1
	v_cndmask_b32_e32 v128, v129, v128, vcc
	v_div_scale_f32 v129, s[2:3], v128, v128, 1.0
	v_rcp_f32_e32 v130, v129
	v_div_scale_f32 v131, vcc, 1.0, v128, 1.0
	v_fma_f32 v132, -v129, v130, 1.0
	v_fmac_f32_e32 v130, v132, v130
	v_mul_f32_e32 v132, v131, v130
	v_fma_f32 v133, -v129, v132, v131
	v_fmac_f32_e32 v132, v133, v130
	v_fma_f32 v129, -v129, v132, v131
	v_div_fmas_f32 v129, v129, v130, v132
	v_div_fixup_f32 v184, v129, v128, 1.0
	s_add_u32 s100, s64, 0x40000
	s_addc_u32 s101, s65, 0
	v_pk_mul_f32 v[220:221], v[92:93], v[184:185] op_sel_hi:[1,0]
	v_pk_mul_f32 v[222:223], v[94:95], v[184:185] op_sel_hi:[1,0]
	v_pk_mul_f32 v[224:225], v[88:89], v[184:185] op_sel_hi:[1,0]
	v_pk_mul_f32 v[226:227], v[90:91], v[184:185] op_sel_hi:[1,0]
	v_pk_mul_f32 v[220:221], v[148:149], v[220:221]
	v_pk_mul_f32 v[222:223], v[150:151], v[222:223]
	v_pk_mul_f32 v[224:225], v[152:153], v[224:225]
	v_pk_mul_f32 v[226:227], v[154:155], v[226:227]
	s_nop 1
	v_permlane16_swap_b32_e32 v220, v224
	v_permlane16_swap_b32_e32 v221, v225
	v_permlane16_swap_b32_e32 v222, v226
	v_permlane16_swap_b32_e32 v223, v227
	v_permlane32_swap_b32_e32 v220, v224
	v_permlane32_swap_b32_e32 v221, v225
	v_permlane32_swap_b32_e32 v222, v226
	v_permlane32_swap_b32_e32 v223, v227
	s_nop 1
	global_store_dwordx4 v185, v[220:223], s[100:101] offset:0
	global_store_dwordx4 v185, v[224:227], s[100:101] offset:64
	v_pk_mul_f32 v[228:229], v[84:85], v[184:185] op_sel_hi:[1,0]
	v_pk_mul_f32 v[230:231], v[86:87], v[184:185] op_sel_hi:[1,0]
	v_pk_mul_f32 v[232:233], v[80:81], v[184:185] op_sel_hi:[1,0]
	v_pk_mul_f32 v[234:235], v[82:83], v[184:185] op_sel_hi:[1,0]
	v_pk_mul_f32 v[228:229], v[156:157], v[228:229]
	v_pk_mul_f32 v[230:231], v[158:159], v[230:231]
	v_pk_mul_f32 v[232:233], v[160:161], v[232:233]
	v_pk_mul_f32 v[234:235], v[162:163], v[234:235]
	s_nop 1
	v_permlane16_swap_b32_e32 v228, v232
	v_permlane16_swap_b32_e32 v229, v233
	v_permlane16_swap_b32_e32 v230, v234
	v_permlane16_swap_b32_e32 v231, v235
	v_permlane32_swap_b32_e32 v228, v232
	v_permlane32_swap_b32_e32 v229, v233
	v_permlane32_swap_b32_e32 v230, v234
	v_permlane32_swap_b32_e32 v231, v235
	s_nop 1
	global_store_dwordx4 v185, v[228:231], s[100:101] offset:512
	global_store_dwordx4 v185, v[232:235], s[100:101] offset:576
	s_waitcnt vmcnt(16)
	v_fmamk_f32 v128, v167, 0x3a000000, v177
	v_mul_f32_e32 v129, 0x4f800000, v128
	v_cmp_gt_f32_e32 vcc, s9, v128
	s_nop 1
	v_cndmask_b32_e32 v128, v128, v129, vcc
	v_sqrt_f32_e32 v129, v128
	s_nop 0
	v_add_u32_e32 v130, -1, v129
	v_add_u32_e32 v131, 1, v129
	v_fma_f32 v132, -v130, v129, v128
	v_fma_f32 v133, -v131, v129, v128
	v_cmp_ge_f32_e64 s[2:3], 0, v132
	s_nop 1
	v_cndmask_b32_e64 v129, v129, v130, s[2:3]
	v_cmp_lt_f32_e64 s[2:3], 0, v133
	s_nop 1
	v_cndmask_b32_e64 v129, v129, v131, s[2:3]
	v_mul_f32_e32 v130, 0x37800000, v129
	v_cndmask_b32_e32 v129, v129, v130, vcc
	v_cmp_class_f32_e32 vcc, v128, v178
	s_nop 1
	v_cndmask_b32_e32 v128, v129, v128, vcc
	v_div_scale_f32 v129, s[2:3], v128, v128, 1.0
	v_rcp_f32_e32 v130, v129
	v_div_scale_f32 v131, vcc, 1.0, v128, 1.0
	v_fma_f32 v132, -v129, v130, 1.0
	v_fmac_f32_e32 v130, v132, v130
	v_mul_f32_e32 v132, v131, v130
	v_fma_f32 v133, -v129, v132, v131
	v_fmac_f32_e32 v132, v133, v130
	v_fma_f32 v129, -v129, v132, v131
	v_div_fmas_f32 v129, v129, v130, v132
	v_div_fixup_f32 v184, v129, v128, 1.0
	s_add_u32 s100, s64, 0x60000
	s_addc_u32 s101, s65, 0
	v_pk_mul_f32 v[236:237], v[76:77], v[184:185] op_sel_hi:[1,0]
	v_pk_mul_f32 v[238:239], v[78:79], v[184:185] op_sel_hi:[1,0]
	v_pk_mul_f32 v[240:241], v[72:73], v[184:185] op_sel_hi:[1,0]
	v_pk_mul_f32 v[242:243], v[74:75], v[184:185] op_sel_hi:[1,0]
	v_pk_mul_f32 v[236:237], v[148:149], v[236:237]
	v_pk_mul_f32 v[238:239], v[150:151], v[238:239]
	v_pk_mul_f32 v[240:241], v[152:153], v[240:241]
	v_pk_mul_f32 v[242:243], v[154:155], v[242:243]
	s_nop 1
	v_permlane16_swap_b32_e32 v236, v240
	v_permlane16_swap_b32_e32 v237, v241
	v_permlane16_swap_b32_e32 v238, v242
	v_permlane16_swap_b32_e32 v239, v243
	v_permlane32_swap_b32_e32 v236, v240
	v_permlane32_swap_b32_e32 v237, v241
	v_permlane32_swap_b32_e32 v238, v242
	v_permlane32_swap_b32_e32 v239, v243
	s_nop 1
	global_store_dwordx4 v185, v[236:239], s[100:101] offset:0
	global_store_dwordx4 v185, v[240:243], s[100:101] offset:64
	v_pk_mul_f32 v[244:245], v[68:69], v[184:185] op_sel_hi:[1,0]
	v_pk_mul_f32 v[246:247], v[70:71], v[184:185] op_sel_hi:[1,0]
	v_pk_mul_f32 v[248:249], v[64:65], v[184:185] op_sel_hi:[1,0]
	v_pk_mul_f32 v[250:251], v[66:67], v[184:185] op_sel_hi:[1,0]
	v_pk_mul_f32 v[244:245], v[156:157], v[244:245]
	v_pk_mul_f32 v[246:247], v[158:159], v[246:247]
	v_pk_mul_f32 v[248:249], v[160:161], v[248:249]
	v_pk_mul_f32 v[250:251], v[162:163], v[250:251]
	s_nop 1
	v_permlane16_swap_b32_e32 v244, v248
	v_permlane16_swap_b32_e32 v245, v249
	v_permlane16_swap_b32_e32 v246, v250
	v_permlane16_swap_b32_e32 v247, v251
	v_permlane32_swap_b32_e32 v244, v248
	v_permlane32_swap_b32_e32 v245, v249
	v_permlane32_swap_b32_e32 v246, v250
	v_permlane32_swap_b32_e32 v247, v251
	s_nop 1
	global_store_dwordx4 v185, v[244:247], s[100:101] offset:512
	global_store_dwordx4 v185, v[248:251], s[100:101] offset:576
	s_waitcnt vmcnt(19)
	v_fmamk_f32 v128, v168, 0x3a000000, v177
	v_mul_f32_e32 v129, 0x4f800000, v128
	v_cmp_gt_f32_e32 vcc, s9, v128
	s_nop 1
	v_cndmask_b32_e32 v128, v128, v129, vcc
	v_sqrt_f32_e32 v129, v128
	s_nop 0
	v_add_u32_e32 v130, -1, v129
	v_add_u32_e32 v131, 1, v129
	v_fma_f32 v132, -v130, v129, v128
	v_fma_f32 v133, -v131, v129, v128
	v_cmp_ge_f32_e64 s[2:3], 0, v132
	s_nop 1
	v_cndmask_b32_e64 v129, v129, v130, s[2:3]
	v_cmp_lt_f32_e64 s[2:3], 0, v133
	s_nop 1
	v_cndmask_b32_e64 v129, v129, v131, s[2:3]
	v_mul_f32_e32 v130, 0x37800000, v129
	v_cndmask_b32_e32 v129, v129, v130, vcc
	v_cmp_class_f32_e32 vcc, v128, v178
	s_nop 1
	v_cndmask_b32_e32 v128, v129, v128, vcc
	v_div_scale_f32 v129, s[2:3], v128, v128, 1.0
	v_rcp_f32_e32 v130, v129
	v_div_scale_f32 v131, vcc, 1.0, v128, 1.0
	v_fma_f32 v132, -v129, v130, 1.0
	v_fmac_f32_e32 v130, v132, v130
	v_mul_f32_e32 v132, v131, v130
	v_fma_f32 v133, -v129, v132, v131
	v_fmac_f32_e32 v132, v133, v130
	v_fma_f32 v129, -v129, v132, v131
	v_div_fmas_f32 v129, v129, v130, v132
	v_div_fixup_f32 v184, v129, v128, 1.0
	s_add_u32 s100, s64, 0x100000
	s_addc_u32 s101, s65, 0
	v_pk_mul_f32 v[188:189], v[60:61], v[184:185] op_sel_hi:[1,0]
	v_pk_mul_f32 v[190:191], v[62:63], v[184:185] op_sel_hi:[1,0]
	v_pk_mul_f32 v[192:193], v[56:57], v[184:185] op_sel_hi:[1,0]
	v_pk_mul_f32 v[194:195], v[58:59], v[184:185] op_sel_hi:[1,0]
	v_pk_mul_f32 v[188:189], v[148:149], v[188:189]
	v_pk_mul_f32 v[190:191], v[150:151], v[190:191]
	v_pk_mul_f32 v[192:193], v[152:153], v[192:193]
	v_pk_mul_f32 v[194:195], v[154:155], v[194:195]
	s_nop 1
	v_permlane16_swap_b32_e32 v188, v192
	v_permlane16_swap_b32_e32 v189, v193
	v_permlane16_swap_b32_e32 v190, v194
	v_permlane16_swap_b32_e32 v191, v195
	v_permlane32_swap_b32_e32 v188, v192
	v_permlane32_swap_b32_e32 v189, v193
	v_permlane32_swap_b32_e32 v190, v194
	v_permlane32_swap_b32_e32 v191, v195
	s_nop 1
	global_store_dwordx4 v185, v[188:191], s[100:101] offset:0
	global_store_dwordx4 v185, v[192:195], s[100:101] offset:64
	v_pk_mul_f32 v[196:197], v[52:53], v[184:185] op_sel_hi:[1,0]
	v_pk_mul_f32 v[198:199], v[54:55], v[184:185] op_sel_hi:[1,0]
	v_pk_mul_f32 v[200:201], v[48:49], v[184:185] op_sel_hi:[1,0]
	v_pk_mul_f32 v[202:203], v[50:51], v[184:185] op_sel_hi:[1,0]
	v_pk_mul_f32 v[196:197], v[156:157], v[196:197]
	v_pk_mul_f32 v[198:199], v[158:159], v[198:199]
	v_pk_mul_f32 v[200:201], v[160:161], v[200:201]
	v_pk_mul_f32 v[202:203], v[162:163], v[202:203]
	s_nop 1
	v_permlane16_swap_b32_e32 v196, v200
	v_permlane16_swap_b32_e32 v197, v201
	v_permlane16_swap_b32_e32 v198, v202
	v_permlane16_swap_b32_e32 v199, v203
	v_permlane32_swap_b32_e32 v196, v200
	v_permlane32_swap_b32_e32 v197, v201
	v_permlane32_swap_b32_e32 v198, v202
	v_permlane32_swap_b32_e32 v199, v203
	s_nop 1
	global_store_dwordx4 v185, v[196:199], s[100:101] offset:512
	global_store_dwordx4 v185, v[200:203], s[100:101] offset:576
	s_waitcnt vmcnt(22)
	v_fmamk_f32 v128, v169, 0x3a000000, v177
	v_mul_f32_e32 v129, 0x4f800000, v128
	v_cmp_gt_f32_e32 vcc, s9, v128
	s_nop 1
	v_cndmask_b32_e32 v128, v128, v129, vcc
	v_sqrt_f32_e32 v129, v128
	s_nop 0
	v_add_u32_e32 v130, -1, v129
	v_add_u32_e32 v131, 1, v129
	v_fma_f32 v132, -v130, v129, v128
	v_fma_f32 v133, -v131, v129, v128
	v_cmp_ge_f32_e64 s[2:3], 0, v132
	s_nop 1
	v_cndmask_b32_e64 v129, v129, v130, s[2:3]
	v_cmp_lt_f32_e64 s[2:3], 0, v133
	s_nop 1
	v_cndmask_b32_e64 v129, v129, v131, s[2:3]
	v_mul_f32_e32 v130, 0x37800000, v129
	v_cndmask_b32_e32 v129, v129, v130, vcc
	v_cmp_class_f32_e32 vcc, v128, v178
	s_nop 1
	v_cndmask_b32_e32 v128, v129, v128, vcc
	v_div_scale_f32 v129, s[2:3], v128, v128, 1.0
	v_rcp_f32_e32 v130, v129
	v_div_scale_f32 v131, vcc, 1.0, v128, 1.0
	v_fma_f32 v132, -v129, v130, 1.0
	v_fmac_f32_e32 v130, v132, v130
	v_mul_f32_e32 v132, v131, v130
	v_fma_f32 v133, -v129, v132, v131
	v_fmac_f32_e32 v132, v133, v130
	v_fma_f32 v129, -v129, v132, v131
	v_div_fmas_f32 v129, v129, v130, v132
	v_div_fixup_f32 v184, v129, v128, 1.0
	s_add_u32 s100, s64, 0x120000
	s_addc_u32 s101, s65, 0
	v_pk_mul_f32 v[204:205], v[44:45], v[184:185] op_sel_hi:[1,0]
	v_pk_mul_f32 v[206:207], v[46:47], v[184:185] op_sel_hi:[1,0]
	v_pk_mul_f32 v[208:209], v[40:41], v[184:185] op_sel_hi:[1,0]
	v_pk_mul_f32 v[210:211], v[42:43], v[184:185] op_sel_hi:[1,0]
	v_pk_mul_f32 v[204:205], v[148:149], v[204:205]
	v_pk_mul_f32 v[206:207], v[150:151], v[206:207]
	v_pk_mul_f32 v[208:209], v[152:153], v[208:209]
	v_pk_mul_f32 v[210:211], v[154:155], v[210:211]
	s_nop 1
	v_permlane16_swap_b32_e32 v204, v208
	v_permlane16_swap_b32_e32 v205, v209
	v_permlane16_swap_b32_e32 v206, v210
	v_permlane16_swap_b32_e32 v207, v211
	v_permlane32_swap_b32_e32 v204, v208
	v_permlane32_swap_b32_e32 v205, v209
	v_permlane32_swap_b32_e32 v206, v210
	v_permlane32_swap_b32_e32 v207, v211
	s_nop 1
	global_store_dwordx4 v185, v[204:207], s[100:101] offset:0
	global_store_dwordx4 v185, v[208:211], s[100:101] offset:64
	v_pk_mul_f32 v[212:213], v[36:37], v[184:185] op_sel_hi:[1,0]
	v_pk_mul_f32 v[214:215], v[38:39], v[184:185] op_sel_hi:[1,0]
	v_pk_mul_f32 v[216:217], v[32:33], v[184:185] op_sel_hi:[1,0]
	v_pk_mul_f32 v[218:219], v[34:35], v[184:185] op_sel_hi:[1,0]
	v_pk_mul_f32 v[212:213], v[156:157], v[212:213]
	v_pk_mul_f32 v[214:215], v[158:159], v[214:215]
	v_pk_mul_f32 v[216:217], v[160:161], v[216:217]
	v_pk_mul_f32 v[218:219], v[162:163], v[218:219]
	s_nop 1
	v_permlane16_swap_b32_e32 v212, v216
	v_permlane16_swap_b32_e32 v213, v217
	v_permlane16_swap_b32_e32 v214, v218
	v_permlane16_swap_b32_e32 v215, v219
	v_permlane32_swap_b32_e32 v212, v216
	v_permlane32_swap_b32_e32 v213, v217
	v_permlane32_swap_b32_e32 v214, v218
	v_permlane32_swap_b32_e32 v215, v219
	s_nop 1
	global_store_dwordx4 v185, v[212:215], s[100:101] offset:512
	global_store_dwordx4 v185, v[216:219], s[100:101] offset:576
	s_waitcnt vmcnt(25)
	v_fmamk_f32 v128, v170, 0x3a000000, v177
	v_mul_f32_e32 v129, 0x4f800000, v128
	v_cmp_gt_f32_e32 vcc, s9, v128
	s_nop 1
	v_cndmask_b32_e32 v128, v128, v129, vcc
	v_sqrt_f32_e32 v129, v128
	s_nop 0
	v_add_u32_e32 v130, -1, v129
	v_add_u32_e32 v131, 1, v129
	v_fma_f32 v132, -v130, v129, v128
	v_fma_f32 v133, -v131, v129, v128
	v_cmp_ge_f32_e64 s[2:3], 0, v132
	s_nop 1
	v_cndmask_b32_e64 v129, v129, v130, s[2:3]
	v_cmp_lt_f32_e64 s[2:3], 0, v133
	s_nop 1
	v_cndmask_b32_e64 v129, v129, v131, s[2:3]
	v_mul_f32_e32 v130, 0x37800000, v129
	v_cndmask_b32_e32 v129, v129, v130, vcc
	v_cmp_class_f32_e32 vcc, v128, v178
	s_nop 1
	v_cndmask_b32_e32 v128, v129, v128, vcc
	v_div_scale_f32 v129, s[2:3], v128, v128, 1.0
	v_rcp_f32_e32 v130, v129
	v_div_scale_f32 v131, vcc, 1.0, v128, 1.0
	v_fma_f32 v132, -v129, v130, 1.0
	v_fmac_f32_e32 v130, v132, v130
	v_mul_f32_e32 v132, v131, v130
	v_fma_f32 v133, -v129, v132, v131
	v_fmac_f32_e32 v132, v133, v130
	v_fma_f32 v129, -v129, v132, v131
	v_div_fmas_f32 v129, v129, v130, v132
	v_div_fixup_f32 v184, v129, v128, 1.0
	s_add_u32 s100, s64, 0x140000
	s_addc_u32 s101, s65, 0
	v_pk_mul_f32 v[220:221], v[28:29], v[184:185] op_sel_hi:[1,0]
	v_pk_mul_f32 v[222:223], v[30:31], v[184:185] op_sel_hi:[1,0]
	v_pk_mul_f32 v[224:225], v[24:25], v[184:185] op_sel_hi:[1,0]
	v_pk_mul_f32 v[226:227], v[26:27], v[184:185] op_sel_hi:[1,0]
	v_pk_mul_f32 v[220:221], v[148:149], v[220:221]
	v_pk_mul_f32 v[222:223], v[150:151], v[222:223]
	v_pk_mul_f32 v[224:225], v[152:153], v[224:225]
	v_pk_mul_f32 v[226:227], v[154:155], v[226:227]
	s_nop 1
	v_permlane16_swap_b32_e32 v220, v224
	v_permlane16_swap_b32_e32 v221, v225
	v_permlane16_swap_b32_e32 v222, v226
	v_permlane16_swap_b32_e32 v223, v227
	v_permlane32_swap_b32_e32 v220, v224
	v_permlane32_swap_b32_e32 v221, v225
	v_permlane32_swap_b32_e32 v222, v226
	v_permlane32_swap_b32_e32 v223, v227
	s_nop 1
	global_store_dwordx4 v185, v[220:223], s[100:101] offset:0
	global_store_dwordx4 v185, v[224:227], s[100:101] offset:64
	v_pk_mul_f32 v[228:229], v[20:21], v[184:185] op_sel_hi:[1,0]
	v_pk_mul_f32 v[230:231], v[22:23], v[184:185] op_sel_hi:[1,0]
	v_pk_mul_f32 v[232:233], v[16:17], v[184:185] op_sel_hi:[1,0]
	v_pk_mul_f32 v[234:235], v[18:19], v[184:185] op_sel_hi:[1,0]
	v_pk_mul_f32 v[228:229], v[156:157], v[228:229]
	v_pk_mul_f32 v[230:231], v[158:159], v[230:231]
	v_pk_mul_f32 v[232:233], v[160:161], v[232:233]
	v_pk_mul_f32 v[234:235], v[162:163], v[234:235]
	s_nop 1
	v_permlane16_swap_b32_e32 v228, v232
	v_permlane16_swap_b32_e32 v229, v233
	v_permlane16_swap_b32_e32 v230, v234
	v_permlane16_swap_b32_e32 v231, v235
	v_permlane32_swap_b32_e32 v228, v232
	v_permlane32_swap_b32_e32 v229, v233
	v_permlane32_swap_b32_e32 v230, v234
	v_permlane32_swap_b32_e32 v231, v235
	s_nop 1
	global_store_dwordx4 v185, v[228:231], s[100:101] offset:512
	global_store_dwordx4 v185, v[232:235], s[100:101] offset:576
	s_waitcnt vmcnt(28)
	v_fmamk_f32 v128, v171, 0x3a000000, v177
	v_mul_f32_e32 v129, 0x4f800000, v128
	v_cmp_gt_f32_e32 vcc, s9, v128
	s_nop 1
	v_cndmask_b32_e32 v128, v128, v129, vcc
	v_sqrt_f32_e32 v129, v128
	s_nop 0
	v_add_u32_e32 v130, -1, v129
	v_add_u32_e32 v131, 1, v129
	v_fma_f32 v132, -v130, v129, v128
	v_fma_f32 v133, -v131, v129, v128
	v_cmp_ge_f32_e64 s[2:3], 0, v132
	s_nop 1
	v_cndmask_b32_e64 v129, v129, v130, s[2:3]
	v_cmp_lt_f32_e64 s[2:3], 0, v133
	s_nop 1
	v_cndmask_b32_e64 v129, v129, v131, s[2:3]
	v_mul_f32_e32 v130, 0x37800000, v129
	v_cndmask_b32_e32 v129, v129, v130, vcc
	v_cmp_class_f32_e32 vcc, v128, v178
	s_nop 1
	v_cndmask_b32_e32 v128, v129, v128, vcc
	v_div_scale_f32 v129, s[2:3], v128, v128, 1.0
	v_rcp_f32_e32 v130, v129
	v_div_scale_f32 v131, vcc, 1.0, v128, 1.0
	v_fma_f32 v132, -v129, v130, 1.0
	v_fmac_f32_e32 v130, v132, v130
	v_mul_f32_e32 v132, v131, v130
	v_fma_f32 v133, -v129, v132, v131
	v_fmac_f32_e32 v132, v133, v130
	v_fma_f32 v129, -v129, v132, v131
	v_div_fmas_f32 v129, v129, v130, v132
	v_div_fixup_f32 v184, v129, v128, 1.0
	s_add_u32 s100, s64, 0x160000
	s_addc_u32 s101, s65, 0
	v_pk_mul_f32 v[236:237], v[12:13], v[184:185] op_sel_hi:[1,0]
	v_pk_mul_f32 v[238:239], v[14:15], v[184:185] op_sel_hi:[1,0]
	v_pk_mul_f32 v[240:241], v[8:9], v[184:185] op_sel_hi:[1,0]
	v_pk_mul_f32 v[242:243], v[10:11], v[184:185] op_sel_hi:[1,0]
	v_pk_mul_f32 v[236:237], v[148:149], v[236:237]
	v_pk_mul_f32 v[238:239], v[150:151], v[238:239]
	v_pk_mul_f32 v[240:241], v[152:153], v[240:241]
	v_pk_mul_f32 v[242:243], v[154:155], v[242:243]
	s_nop 1
	v_permlane16_swap_b32_e32 v236, v240
	v_permlane16_swap_b32_e32 v237, v241
	v_permlane16_swap_b32_e32 v238, v242
	v_permlane16_swap_b32_e32 v239, v243
	v_permlane32_swap_b32_e32 v236, v240
	v_permlane32_swap_b32_e32 v237, v241
	v_permlane32_swap_b32_e32 v238, v242
	v_permlane32_swap_b32_e32 v239, v243
	s_nop 1
	global_store_dwordx4 v185, v[236:239], s[100:101] offset:0
	global_store_dwordx4 v185, v[240:243], s[100:101] offset:64
	v_pk_mul_f32 v[244:245], v[4:5], v[184:185] op_sel_hi:[1,0]
	v_pk_mul_f32 v[246:247], v[6:7], v[184:185] op_sel_hi:[1,0]
	v_pk_mul_f32 v[248:249], v[0:1], v[184:185] op_sel_hi:[1,0]
	v_pk_mul_f32 v[250:251], v[2:3], v[184:185] op_sel_hi:[1,0]
	v_pk_mul_f32 v[244:245], v[156:157], v[244:245]
	v_pk_mul_f32 v[246:247], v[158:159], v[246:247]
	v_pk_mul_f32 v[248:249], v[160:161], v[248:249]
	v_pk_mul_f32 v[250:251], v[162:163], v[250:251]
	s_nop 1
	v_permlane16_swap_b32_e32 v244, v248
	v_permlane16_swap_b32_e32 v245, v249
	v_permlane16_swap_b32_e32 v246, v250
	v_permlane16_swap_b32_e32 v247, v251
	v_permlane32_swap_b32_e32 v244, v248
	v_permlane32_swap_b32_e32 v245, v249
	v_permlane32_swap_b32_e32 v246, v250
	v_permlane32_swap_b32_e32 v247, v251
	s_nop 1
	global_store_dwordx4 v185, v[244:247], s[100:101] offset:512
	global_store_dwordx4 v185, v[248:251], s[100:101] offset:576
	s_andn2_b64 vcc, exec, s[22:23]
	s_mov_b64 s[2:3], -1
	s_cbranch_vccnz .LBB0_672
	s_and_b64 vcc, exec, s[0:1]
	s_cbranch_vccnz .LBB0_671
	s_barrier
	s_branch .LBB0_671
